# grid barrier: XCD-local release (skip top-level counter) for barriers between phases whose rows are owned by one XCD group, guarded by a start-up blockIdx%8==XCC_ID check
# baseline (speedup 1.0000x reference)
_Z14fwd_megakernel1P:
	s_load_dwordx8 s[4:11], s[0:1], 0x100
	s_load_dword s52, s[0:1], 0x138
	s_load_dwordx4 s[88:91], s[0:1], 0x120
	s_load_dwordx2 s[96:97], s[0:1], 0x130
	v_writelane_b32 v252, s2, 0
	s_add_u32 s2, s0, 0x130
	v_and_b32_e32 v228, 0x3ff, v0
	s_waitcnt lgkmcnt(0)
	v_writelane_b32 v252, s4, 1
	s_addc_u32 s3, s1, 0
	s_nop 0
	v_writelane_b32 v252, s5, 2
	v_writelane_b32 v252, s6, 3
	v_writelane_b32 v252, s7, 4
	v_writelane_b32 v252, s8, 5
	v_writelane_b32 v252, s9, 6
	v_writelane_b32 v252, s10, 7
	v_writelane_b32 v252, s11, 8
	v_cmp_eq_u32_e64 s[10:11], 0, v228
	s_and_saveexec_b64 s[4:5], s[10:11]
	v_mov_b32_e32 v2, 0
	v_mov_b32_e32 v3, v2
	v_mov_b32_e32 v4, v2
	v_mov_b32_e32 v5, v2
	ds_write_b128 v2, v[2:5] offset:61440
	s_or_b64 exec, exec, s[4:5]
	s_add_u32 s4, s90, 0x1794c000
	s_addc_u32 s5, s91, 0
	v_writelane_b32 v252, s4, 9
	s_waitcnt lgkmcnt(0)
	s_barrier
	v_writelane_b32 v252, s5, 10
	v_writelane_b32 v252, s10, 11
	s_getreg_b32 s8, hwreg(HW_REG_XCC_ID, 0, 4)
	s_nop 0
	v_writelane_b32 v252, s11, 12
	s_and_saveexec_b64 s[4:5], s[10:11]
	s_cbranch_execz .LBB0_5
	s_mov_b64 s[6:7], exec
	v_mbcnt_lo_u32_b32 v1, s6, 0
	v_mbcnt_hi_u32_b32 v1, s7, v1
	v_cmp_eq_u32_e32 vcc, 0, v1
	s_and_b64 s[10:11], exec, vcc
	s_mov_b64 exec, s[10:11]
	s_cbranch_execz .LBB0_5
	v_readlane_b32 s9, v252, 0
	s_and_b32 s9, s9, 7
	s_cmp_eq_u32 s9, s8
	s_cbranch_scc1 .Lxb_match
	v_readlane_b32 s12, v252, 9
	v_readlane_b32 s13, v252, 10
	v_mov_b32_e32 v3, 1
	v_mov_b32_e32 v4, 0
	s_nop 4
	global_atomic_add v4, v3, s[12:13] offset:768
.Lxb_match:
	s_lshl_b32 s8, s8, 8
	s_bcnt1_i32_b64 s6, s[6:7]
	s_and_b32 s8, s8, 0xf00
	v_mov_b32_e32 v2, s6
	v_readlane_b32 s6, v252, 9
	v_mov_b32_e32 v1, s8
	v_readlane_b32 s7, v252, 10
	s_nop 4
	global_atomic_add v1, v2, s[6:7] offset:1024

.LBB0_188:
	s_or_b64 exec, exec, s[0:1]
	s_add_u32 s44, s90, 0x9148000
	s_addc_u32 s45, s91, 0
	s_add_u32 s40, s90, 0x7148000
	s_addc_u32 s41, s91, 0
	s_ashr_i32 s4, s96, 3
	s_add_u32 s42, s90, 0x1794c200
	s_addc_u32 s43, s91, 0
	s_add_u32 s56, s90, 0x1794c400
	s_addc_u32 s57, s91, 0
	s_add_u32 s58, s90, 0x1794c500
	s_addc_u32 s59, s91, 0
	s_add_u32 s60, s90, 0x1794c600
	s_addc_u32 s61, s91, 0
	s_add_u32 s62, s90, 0x1794c700
	s_addc_u32 s63, s91, 0
	s_add_u32 s64, s90, 0x1794c800
	s_addc_u32 s65, s91, 0
	s_add_u32 s26, s90, 0x1794c900
	s_addc_u32 s27, s91, 0
	s_add_u32 s0, s90, 0x1794ca00
	s_addc_u32 s1, s91, 0
	v_writelane_b32 v253, s0, 20
	v_readlane_b32 s2, v252, 0
	s_mul_i32 s68, s97, s96
	v_writelane_b32 v253, s1, 21
	s_add_u32 s0, s90, 0x1794cb00
	s_addc_u32 s1, s91, 0
	v_writelane_b32 v253, s0, 22
	s_mul_i32 s68, s68, s52
	v_mov_b32_e32 v197, 0
	v_writelane_b32 v253, s1, 23
	s_add_u32 s0, s90, 0x1794cc00
	s_addc_u32 s1, s91, 0
	v_writelane_b32 v253, s0, 24
	v_mov_b32_e32 v229, 0x358637bd
	v_mov_b32_e32 v234, 0x1000
	v_writelane_b32 v253, s1, 25
	s_add_u32 s0, s90, 0x1794cd00
	s_addc_u32 s1, s91, 0
	v_writelane_b32 v253, s0, 26
	v_mov_b32_e32 v236, 0x2000
	v_mov_b32_e32 v235, 0xf149f2ca
	v_writelane_b32 v253, s1, 27
	s_add_u32 s0, s90, 0x1794ce00
	s_addc_u32 s1, s91, 0
	v_writelane_b32 v253, s0, 28
	v_mov_b32_e32 v237, 0x41b17218
	s_movk_i32 s28, 0x1800
	v_writelane_b32 v253, s1, 29
	s_add_u32 s0, s90, 0x1794cf00
	s_addc_u32 s1, s91, 0
	v_writelane_b32 v253, s0, 30
	s_movk_i32 s22, 0x1fff
	s_mov_b32 s69, 0x800000
	v_writelane_b32 v253, s1, 31
	s_add_u32 s0, s90, 0x1794d000
	s_addc_u32 s1, s91, 0
	v_writelane_b32 v253, s0, 32
	s_movk_i32 s70, 0x1a00
	s_mov_b32 s30, 0xf149f2ca
	v_writelane_b32 v253, s1, 33
	s_add_u32 s0, s90, 0x1794d100
	s_addc_u32 s1, s91, 0
	v_writelane_b32 v253, s0, 34
	s_movk_i32 s47, 0x1000
	s_mov_b32 s71, 0xbfb8aa3b
	v_writelane_b32 v253, s1, 35
	s_add_u32 s0, s90, 0x1794d200
	s_addc_u32 s1, s91, 0
	v_writelane_b32 v253, s0, 36
	s_mov_b32 s38, 0x3f317217
	s_mov_b32 s39, 0x7f800000
	v_writelane_b32 v253, s1, 37
	s_add_u32 s0, s90, 0x1794d300
	s_addc_u32 s1, s91, 0
	v_writelane_b32 v253, s0, 38
	s_movk_i32 s46, 0x1600
	s_mov_b32 s51, 0
	v_writelane_b32 v253, s1, 39
	s_add_u32 s0, s90, 0x1794f400
	s_addc_u32 s1, s91, 0
	v_writelane_b32 v253, s0, 40
	s_mov_b32 s52, 0x3c800000
	s_waitcnt lgkmcnt(0)
	v_writelane_b32 v253, s1, 41
	s_add_u32 s0, s90, 0x1794f500
	s_addc_u32 s1, s91, 0
	s_lshr_b32 s53, s96, 3
	v_writelane_b32 v253, s0, 42
	s_cmpk_lt_u32 s2, 0xc00
	s_barrier
	v_writelane_b32 v253, s1, 43
	s_cselect_b64 s[0:1], -1, 0
	v_writelane_b32 v253, s0, 44
	s_lshr_b32 s3, s2, 3
	s_nop 0
	v_writelane_b32 v253, s1, 45
	s_lshl_b32 s0, s2, 4
	s_and_b32 s0, s0, 0x70
	s_cmpk_lt_u32 s2, 0x680
	v_writelane_b32 v253, s0, 46
	s_cselect_b64 s[0:1], -1, 0
	v_writelane_b32 v253, s0, 47
	s_nop 1
	v_writelane_b32 v253, s1, 48
	s_add_u32 s6, s90, 0x1794c300
	s_addc_u32 s7, s91, 0
	v_mov_b32_e32 v1, 0
	global_load_dword v1, v1, s[6:7] sc1
	s_waitcnt vmcnt(0)
	v_readfirstlane_b32 s6, v1
	s_cmp_eq_u32 s6, 0
	s_cselect_b32 s6, 1, 0
	s_nop 0
	v_writelane_b32 v255, s6, 12
	s_lshl_b32 s0, s2, 3
	s_and_b32 s33, s0, 56
	s_add_i32 s0, s96, 0xbff
	v_writelane_b32 v253, s0, 49
	s_ashr_i32 s0, s96, 1
	s_add_u32 s94, s90, 0x7048000
	s_addc_u32 s95, s91, 0
	s_add_u32 s48, s90, 0x13948000
	s_addc_u32 s49, s91, 0
	s_add_u32 s92, s90, 0xf948000
	s_addc_u32 s93, s91, 0
	s_cmpk_lt_i32 s96, 0x101
	v_writelane_b32 v253, s0, 50
	s_cselect_b64 s[0:1], -1, 0
	v_writelane_b32 v253, s0, 51
	s_nop 1
	v_writelane_b32 v253, s1, 52
	s_add_u32 s0, s88, 0x8000000
	v_writelane_b32 v253, s0, 53
	s_addc_u32 s0, s89, 0
	v_writelane_b32 v253, s0, 54
	s_add_i32 s0, s96, 0xffffff80
	v_writelane_b32 v253, s0, 55
	s_add_u32 s0, s90, 0x7148400
	s_addc_u32 s1, s91, 0
	v_writelane_b32 v253, s0, 56
	s_cmpk_lt_u32 s2, 0xb00
	s_nop 0
	v_writelane_b32 v253, s1, 57
	s_cselect_b64 s[0:1], -1, 0
	v_writelane_b32 v253, s0, 58
	s_cmpk_lt_u32 s2, 0x200
	s_nop 0
	v_writelane_b32 v253, s1, 59
	s_cselect_b64 s[0:1], -1, 0
	v_writelane_b32 v253, s0, 60
	s_cmp_lt_u32 s33, 32
	s_nop 0
	v_writelane_b32 v253, s1, 61
	s_cselect_b64 s[0:1], -1, 0
	v_writelane_b32 v253, s0, 62
	s_lshl_b32 s35, s4, 2
	s_nop 0
	v_writelane_b32 v253, s1, 63
	s_abs_i32 s0, s96
	v_cvt_f32_u32_e32 v0, s0
	s_ashr_i32 s1, s96, 31
	v_writelane_b32 v254, s1, 0
	v_writelane_b32 v254, s0, 1
	v_rcp_iflag_f32_e32 v0, v0
	s_sub_i32 s0, 0, s0
	v_mul_f32_e32 v0, 0x4f7ffffe, v0
	v_cvt_u32_f32_e32 v0, v0
	s_nop 0
	v_readfirstlane_b32 s1, v0
	s_mul_i32 s0, s0, s1
	s_mul_hi_u32 s0, s1, s0
	s_add_i32 s0, s1, s0
	v_writelane_b32 v254, s0, 2
	s_add_u32 s0, s90, 0x7148080
	v_writelane_b32 v254, s4, 3
	s_addc_u32 s1, s91, 0
	v_writelane_b32 v254, s0, 4
	s_nop 1
	v_writelane_b32 v254, s1, 5
	s_lshl_b32 s0, s2, 11
	s_and_b32 s0, s0, 0x3800
	s_or_b32 s1, s0, 32
	v_writelane_b32 v254, s1, 6
	s_or_b32 s1, s0, 64
	v_writelane_b32 v254, s1, 7
	s_or_b32 s1, s0, 0x60
	s_add_u32 s4, s90, 0x1100080
	v_writelane_b32 v254, s1, 8
	s_addc_u32 s5, s91, 0
	v_writelane_b32 v254, s4, 9
	s_and_b32 s1, s2, -8
	s_nop 0
	v_writelane_b32 v254, s5, 10
	v_writelane_b32 v254, s1, 11
	s_and_b32 s1, s96, -8
	v_writelane_b32 v254, s1, 12
	s_or_b32 s1, s0, 0x80
	v_writelane_b32 v254, s1, 13
	s_or_b32 s1, s0, 0xa0
	v_writelane_b32 v254, s1, 14
	s_or_b32 s1, s0, 0xc0
	v_writelane_b32 v254, s1, 15
	v_writelane_b32 v254, s0, 16
	s_or_b32 s0, s0, 0xe0
	v_writelane_b32 v254, s0, 17
	s_add_u32 s0, s90, 0x80
	v_writelane_b32 v254, s0, 18
	s_addc_u32 s0, s91, 0
	v_writelane_b32 v254, s0, 19
	v_writelane_b32 v254, s3, 20
	s_lshl_b32 s0, s3, 4
	v_writelane_b32 v254, s0, 21
	s_lshl_b32 s0, s53, 4
	v_writelane_b32 v254, s0, 22
	s_add_u32 s0, s90, 0x2100080
	s_addc_u32 s1, s91, 0
	v_writelane_b32 v254, s0, 23
	s_mov_b64 s[2:3], 0
	s_nop 0
	v_writelane_b32 v254, s1, 24
	v_writelane_b32 v254, s35, 25
	v_writelane_b32 v254, s40, 26
	s_nop 1
	v_writelane_b32 v254, s41, 27
	v_writelane_b32 v254, s42, 28
	s_nop 1
	v_writelane_b32 v254, s43, 29
	v_writelane_b32 v254, s56, 30
	s_nop 1
	v_writelane_b32 v254, s57, 31
	v_writelane_b32 v254, s58, 32
	s_nop 1
	v_writelane_b32 v254, s59, 33
	v_writelane_b32 v254, s60, 34
	s_nop 1
	v_writelane_b32 v254, s61, 35
	v_writelane_b32 v254, s62, 36
	s_nop 1
	v_writelane_b32 v254, s63, 37
	v_writelane_b32 v254, s64, 38
	s_nop 1
	v_writelane_b32 v254, s65, 39
	v_writelane_b32 v254, s26, 40
	s_nop 1
	v_writelane_b32 v254, s27, 41
	v_writelane_b32 v254, s96, 42
	s_nop 1
	v_writelane_b32 v254, s97, 43
	s_branch .LBB0_190

.LBB0_225:
	s_andn2_saveexec_b64 s[2:3], s[6:7]
	s_cbranch_execz .LBB0_245
	s_mov_b64 s[6:7], exec
	buffer_wbl2 sc1
	s_waitcnt lgkmcnt(0)
	s_waitcnt vmcnt(0)
	v_readlane_b32 s2, v255, 12
	s_cmp_lg_u32 s2, 0
	s_cbranch_scc1 .Lxb_local_0
	v_mbcnt_lo_u32_b32 v1, s6, 0
	v_mbcnt_hi_u32_b32 v1, s7, v1
	v_cmp_eq_u32_e32 vcc, 0, v1
	s_and_saveexec_b64 s[8:9], vcc
	s_cbranch_execz .LBB0_228
	s_bcnt1_i32_b64 s2, s[6:7]
	v_mov_b32_e32 v2, s2
	v_readlane_b32 s2, v253, 40
	v_readlane_b32 s3, v253, 41
	s_nop 4
	global_atomic_add v2, v197, v2, s[2:3] sc0

.Lxb_local_0:
	s_mov_b64 s[6:7], exec
	v_mbcnt_lo_u32_b32 v0, s6, 0
	v_mbcnt_hi_u32_b32 v0, s7, v0
	v_cmp_eq_u32_e32 vcc, 0, v0
	s_waitcnt vmcnt(0)
	buffer_inv sc1
	s_and_saveexec_b64 s[8:9], vcc
	s_cbranch_execz .LBB0_244
	s_bcnt1_i32_b64 s2, s[6:7]
	v_mov_b32_e32 v0, s2
	global_atomic_add v236, v0, s[4:5] offset:1024

.LBB0_828:
	s_andn2_saveexec_b64 s[2:3], s[12:13]
	s_cbranch_execz .LBB0_848
	s_mov_b64 s[12:13], exec
	buffer_wbl2 sc1
	s_waitcnt lgkmcnt(0)
	s_waitcnt vmcnt(0)
	v_readlane_b32 s2, v255, 12
	s_cmp_lg_u32 s2, 0
	s_cbranch_scc1 .Lxb_local_5
	v_mbcnt_lo_u32_b32 v1, s12, 0
	v_mbcnt_hi_u32_b32 v1, s13, v1
	v_cmp_eq_u32_e32 vcc, 0, v1
	s_and_saveexec_b64 s[14:15], vcc
	s_cbranch_execz .LBB0_831
	s_bcnt1_i32_b64 s2, s[12:13]
	v_mov_b32_e32 v2, s2
	v_readlane_b32 s2, v253, 40
	v_readlane_b32 s3, v253, 41
	s_nop 4
	global_atomic_add v2, v197, v2, s[2:3] sc0

.Lxb_local_5:
	s_mov_b64 s[12:13], exec
	v_mbcnt_lo_u32_b32 v0, s12, 0
	v_mbcnt_hi_u32_b32 v0, s13, v0
	v_cmp_eq_u32_e32 vcc, 0, v0
	s_waitcnt vmcnt(0)
	buffer_inv sc1
	s_and_saveexec_b64 s[14:15], vcc
	s_cbranch_execz .LBB0_847
	s_bcnt1_i32_b64 s2, s[12:13]
	v_mov_b32_e32 v0, s2
	global_atomic_add v236, v0, s[10:11] offset:1024

.LBB0_885:
	s_andn2_saveexec_b64 s[12:13], s[12:13]
	s_cbranch_execz .LBB0_905
	s_mov_b64 s[14:15], exec
	buffer_wbl2 sc1
	s_waitcnt lgkmcnt(0)
	s_waitcnt vmcnt(0)
	v_readlane_b32 s2, v255, 12
	s_cmp_lg_u32 s2, 0
	s_cbranch_scc1 .Lxb_local_6
	v_mbcnt_lo_u32_b32 v1, s14, 0
	v_mbcnt_hi_u32_b32 v1, s15, v1
	v_cmp_eq_u32_e32 vcc, 0, v1
	s_and_saveexec_b64 s[16:17], vcc
	s_cbranch_execz .LBB0_888
	s_bcnt1_i32_b64 s2, s[14:15]
	v_mov_b32_e32 v2, s2
	v_readlane_b32 s2, v253, 40
	v_readlane_b32 s3, v253, 41
	s_nop 4
	global_atomic_add v2, v197, v2, s[2:3] sc0

.Lxb_local_6:
	s_mov_b64 s[14:15], exec
	v_mbcnt_lo_u32_b32 v0, s14, 0
	v_mbcnt_hi_u32_b32 v0, s15, v0
	v_cmp_eq_u32_e32 vcc, 0, v0
	s_waitcnt vmcnt(0)
	buffer_inv sc1
	s_and_saveexec_b64 s[16:17], vcc
	s_cbranch_execz .LBB0_904
	s_bcnt1_i32_b64 s2, s[14:15]
	v_mov_b32_e32 v0, s2
	global_atomic_add v236, v0, s[10:11] offset:1024

.Lxb_local_7:
	s_mov_b64 s[12:13], exec
	v_mbcnt_lo_u32_b32 v0, s12, 0
	v_mbcnt_hi_u32_b32 v0, s13, v0
	v_cmp_eq_u32_e32 vcc, 0, v0
	s_waitcnt vmcnt(0)
	buffer_inv sc1
	s_and_saveexec_b64 s[14:15], vcc
	s_cbranch_execz .LBB0_791
	s_bcnt1_i32_b64 s2, s[12:13]
	v_mov_b32_e32 v0, s2
	global_atomic_add v236, v0, s[10:11] offset:1024
	s_branch .LBB0_791
